# attention B far loop: mask bit extraction moved to v_bfe_i32 at the former v_and position (all 32 ands and cmps gone)
# speedup vs baseline: 1.0104x; 1.0104x over previous
; template <int DQK, bool MB> ...
;     ...
;                 const unsigned long long mw0 = sm0[kt], mw1 = sm1[kt];
;                 if (pass == 0) {
; #pragma unroll
;                     for (int ks = 0; ks < 4; ++ks) { const unsigned b0 = (unsigned)(mw0 >> (16 * ks + 4 * q)) & 0xFu, b1 = (unsigned)(mw1 >> (16 * ks + 4 * q)) & 0xFu;
; #pragma unroll
;                         for (int j = 0; j < 4; ++j) { s[ks][0][j] = ((b0 >> j) & 1u) ? s[ks][0][j] + tbfar : -INFINITY; s[ks][1][j] = ((b1 >> j) & 1u) ? s[ks][1][j] + tbfar : -INFINITY; } }
.LBB0_665:
	v_lshl_add_u32 v156, s45, 14, v181
	ds_read_b128 v[124:127], v156
	ds_read_b128 v[128:131], v156 offset:1024
	ds_read_b128 v[132:135], v156 offset:2048
	ds_read_b128 v[136:139], v156 offset:3072
	ds_read_b128 v[140:143], v156 offset:4096
	ds_read_b128 v[160:163], v156 offset:5120
	ds_read_b128 v[164:167], v156 offset:6144
	ds_read_b128 v[186:189], v156 offset:7168
	s_waitcnt lgkmcnt(7)
	v_mfma_f32_16x16x32_bf16 v[190:193], v[124:127], v[44:47], 0
	v_mfma_f32_16x16x32_bf16 v[124:127], v[124:127], v[60:63], 0
	s_waitcnt lgkmcnt(6)
	v_mfma_f32_16x16x32_bf16 v[190:193], v[128:131], v[64:67], v[190:193]
	v_mfma_f32_16x16x32_bf16 v[124:127], v[128:131], v[72:75], v[124:127]
	s_waitcnt lgkmcnt(5)
	v_mfma_f32_16x16x32_bf16 v[128:131], v[132:135], v[68:71], v[190:193]
	v_mfma_f32_16x16x32_bf16 v[124:127], v[132:135], v[76:79], v[124:127]
	s_waitcnt lgkmcnt(4)
	v_mfma_f32_16x16x32_bf16 v[128:131], v[136:139], v[80:83], v[128:131]
	v_mfma_f32_16x16x32_bf16 v[124:127], v[136:139], v[56:59], v[124:127]
	ds_read_b128 v[132:135], v156 offset:8192
	ds_read_b128 v[136:139], v156 offset:9216
	ds_read_b128 v[190:193], v156 offset:10240
	ds_read_b128 v[194:197], v156 offset:11264
	s_waitcnt lgkmcnt(7)
	v_mfma_f32_16x16x32_bf16 v[198:201], v[140:143], v[44:47], 0
	v_mfma_f32_16x16x32_bf16 v[140:143], v[140:143], v[60:63], 0
	s_waitcnt lgkmcnt(6)
	v_mfma_f32_16x16x32_bf16 v[198:201], v[160:163], v[64:67], v[198:201]
	v_mfma_f32_16x16x32_bf16 v[140:143], v[160:163], v[72:75], v[140:143]
	s_waitcnt lgkmcnt(5)
	v_mfma_f32_16x16x32_bf16 v[160:163], v[164:167], v[68:71], v[198:201]
	v_mfma_f32_16x16x32_bf16 v[140:143], v[164:167], v[76:79], v[140:143]
	s_waitcnt lgkmcnt(4)
	v_mfma_f32_16x16x32_bf16 v[160:163], v[186:189], v[80:83], v[160:163]
	v_mfma_f32_16x16x32_bf16 v[140:143], v[186:189], v[56:59], v[140:143]
	ds_read_b128 v[164:167], v156 offset:12288
	ds_read_b128 v[186:189], v156 offset:13312
	ds_read_b128 v[198:201], v156 offset:14336
	ds_read_b128 v[202:205], v156 offset:15360
	s_waitcnt lgkmcnt(7)
	v_mfma_f32_16x16x32_bf16 v[206:209], v[132:135], v[44:47], 0
	v_mfma_f32_16x16x32_bf16 v[132:135], v[132:135], v[60:63], 0
	s_waitcnt lgkmcnt(6)
	v_mfma_f32_16x16x32_bf16 v[206:209], v[136:139], v[64:67], v[206:209]
	v_mfma_f32_16x16x32_bf16 v[132:135], v[136:139], v[72:75], v[132:135]
	s_waitcnt lgkmcnt(5)
	v_mfma_f32_16x16x32_bf16 v[136:139], v[190:193], v[68:71], v[206:209]
	v_mfma_f32_16x16x32_bf16 v[132:135], v[190:193], v[76:79], v[132:135]
	s_waitcnt lgkmcnt(4)
	v_mfma_f32_16x16x32_bf16 v[136:139], v[194:197], v[80:83], v[136:139]
	v_mfma_f32_16x16x32_bf16 v[132:135], v[194:197], v[56:59], v[132:135]
	s_waitcnt lgkmcnt(3)
	v_mfma_f32_16x16x32_bf16 v[190:193], v[164:167], v[44:47], 0
	v_mfma_f32_16x16x32_bf16 v[164:167], v[164:167], v[60:63], 0
	s_waitcnt lgkmcnt(2)
	v_mfma_f32_16x16x32_bf16 v[164:167], v[186:189], v[72:75], v[164:167]
	v_mfma_f32_16x16x32_bf16 v[190:193], v[186:189], v[64:67], v[190:193]
	s_waitcnt lgkmcnt(1)
	v_mfma_f32_16x16x32_bf16 v[164:167], v[198:201], v[76:79], v[164:167]
	v_mfma_f32_16x16x32_bf16 v[186:189], v[198:201], v[68:71], v[190:193]
	s_waitcnt lgkmcnt(0)
	v_mfma_f32_16x16x32_bf16 v[164:167], v[202:205], v[56:59], v[164:167]
	v_mfma_f32_16x16x32_bf16 v[186:189], v[202:205], v[80:83], v[186:189]
	v_mov_b32_e32 v156, s4
	s_nop 0
	ds_read2_b64 v[190:193], v156 offset1:32
	s_nop 3
	v_add_f32_e32 v158, v113, v164
	v_add_f32_e32 v164, v113, v165
	v_add_f32_e32 v132, v113, v132
	v_add_f32_e32 v124, v113, v124
	s_waitcnt lgkmcnt(0)
	v_lshrrev_b64 v[156:157], v150, v[192:193]
	v_bfe_i32 v243, v156, 0, 1
	v_bfe_i32 v244, v156, 1, 1
	v_add_f32_e32 v126, v113, v126
	v_bfi_b32 v168, v243, v158, v155
	v_bfe_i32 v245, v156, 2, 1
	v_add_f32_e32 v157, v113, v166
	v_bfi_b32 v169, v244, v164, v155
	v_bfe_i32 v246, v156, 3, 1
	v_add_f32_e32 v127, v113, v127
	v_bfi_b32 v166, v245, v157, v155
	v_add_f32_e32 v157, v113, v167
	s_mul_i32 s47, s45, 0x4400
	v_bfi_b32 v185, v246, v157, v155
	v_lshrrev_b64 v[156:157], v150, v[190:191]
	v_bfe_i32 v247, v156, 0, 1
	v_add_f32_e32 v157, v113, v186
	v_bfe_i32 v243, v156, 1, 1
	v_bfe_i32 v244, v156, 2, 1
	v_bfi_b32 v158, v247, v157, v155
	v_add_f32_e32 v157, v113, v187
	v_bfe_i32 v245, v156, 3, 1
	v_bfi_b32 v164, v243, v157, v155
	v_add_f32_e32 v157, v113, v188
	v_bfi_b32 v167, v244, v157, v155
	v_add_f32_e32 v157, v113, v189
	v_bfi_b32 v183, v245, v157, v155
	v_lshrrev_b64 v[156:157], v152, v[192:193]
	v_bfe_i32 v246, v156, 0, 1
	v_bfi_b32 v186, v246, v132, v155
	v_add_f32_e32 v132, v113, v133
	v_bfe_i32 v247, v156, 1, 1
	v_bfe_i32 v243, v156, 2, 1
	v_bfi_b32 v187, v247, v132, v155
	v_add_f32_e32 v132, v113, v134
	v_bfe_i32 v244, v156, 3, 1
	v_bfi_b32 v188, v243, v132, v155
	v_add_f32_e32 v132, v113, v135
	v_bfi_b32 v189, v244, v132, v155
	v_lshrrev_b64 v[132:133], v152, v[190:191]
	v_bfe_i32 v245, v132, 0, 1
	v_add_f32_e32 v133, v113, v136
	v_bfe_i32 v246, v132, 1, 1
	v_bfi_b32 v134, v245, v133, v155
	v_add_f32_e32 v133, v113, v137
	v_bfe_i32 v247, v132, 2, 1
	v_bfe_i32 v243, v132, 3, 1
	v_bfi_b32 v136, v246, v133, v155
	v_add_f32_e32 v133, v113, v138
	v_lshrrev_b32_e32 v135, v154, v192
	v_bfe_i32 v244, v135, 0, 1
	v_bfi_b32 v138, v247, v133, v155
	v_add_f32_e32 v133, v113, v139
	v_bfi_b32 v156, v243, v133, v155
	v_lshrrev_b64 v[132:133], v154, v[192:193]
	v_add_f32_e32 v133, v113, v140
	v_bfe_i32 v245, v132, 1, 1
	v_bfi_b32 v194, v244, v133, v155
	v_add_f32_e32 v133, v113, v141
	v_bfe_i32 v246, v132, 2, 1
	v_bfe_i32 v247, v132, 3, 1
	v_bfi_b32 v195, v245, v133, v155
	v_add_f32_e32 v133, v113, v142
	v_lshrrev_b32_e32 v135, v154, v190
	v_bfe_i32 v243, v135, 0, 1
	v_bfi_b32 v196, v246, v133, v155
; template <int DQK, bool MB> ...
;     ...
;                 if (pass == 0) {
; #pragma unroll
;                     for (int ks = 0; ks < 4; ++ks) { const unsigned b0 = (unsigned)(mw0 >> (16 * ks + 4 * q)) & 0xFu, b1 = (unsigned)(mw1 >> (16 * ks + 4 * q)) & 0xFu;
; #pragma unroll
;                         for (int j = 0; j < 4; ++j) { s[ks][0][j] = ((b0 >> j) & 1u) ? s[ks][0][j] + tbfar : -INFINITY; s[ks][1][j] = ((b1 >> j) & 1u) ? s[ks][1][j] + tbfar : -INFINITY; } }
;                 } else
;                 {
;                 float bv[4][2][4];
; #pragma unroll
;                 for (int ks = 0; ks < 4; ++ks) { const i32x4 pk = *(const i32x4*)(posb + 64 * kt + 16 * ks + 4 * q);
; #pragma unroll
;                     for (int j = 0; j < 4; ++j) { const int d0 = min(max(pt0 - pk[j], 0), 128), d1 = min(max(pt1 - pk[j], 0), 128);
;                         bv[ks][0][j] = tb[d0 * 16 + r]; bv[ks][1][j] = tb[d1 * 16 + r]; } }
;                 __builtin_amdgcn_sched_barrier(0);
; #pragma unroll
;                 for (int ks = 0; ks < 4; ++ks) { const unsigned b0 = (unsigned)(mw0 >> (16 * ks + 4 * q)) & 0xFu, b1 = (unsigned)(mw1 >> (16 * ks + 4 * q)) & 0xFu;
; #pragma unroll
;                     for (int j = 0; j < 4; ++j) { s[ks][0][j] = ((b0 >> j) & 1u) ? s[ks][0][j] + bv[ks][0][j] : -INFINITY; s[ks][1][j] = ((b1 >> j) & 1u) ? s[ks][1][j] + bv[ks][1][j] : -INFINITY; } }
;                 }
;             } else if (64 * kt + 63 > wave_qmax - 31) {
; #pragma unroll
;                 for (int ks = 0; ks < 4; ++ks)
; #pragma unroll
;                     for (int j = 0; j < 4; ++j) { const int key = 64 * kt + 16 * ks + 4 * q + j;
;                         s[ks][0][j] = (key <= qi0) ? s[ks][0][j] : -INFINITY; s[ks][1][j] = (key <= qi1) ? s[ks][1][j] : -INFINITY; }
;             }
;             float alpha2[2];
; #pragma unroll
;             for (int ct = 0; ct < 2; ++ct) {
;                 float mx = -INFINITY;
; #pragma unroll
;                 for (int ks = 0; ks < 4; ++ks)
; #pragma unroll
;                     for (int j = 0; j < 4; ++j) mx = fmaxf(mx, s[ks][ct][j]);
;                 mx = fmaxf(mx, __shfl_xor(mx, 16)); mx = fmaxf(mx, __shfl_xor(mx, 32));
;                 const float mnew = fmaxf(mrow[ct], mx), alpha = __builtin_amdgcn_exp2f(mrow[ct] - mnew);
;                 mrow[ct] = mnew;
;                 float ps = 0.f;
; #pragma unroll
	v_add_f32_e32 v133, v113, v143
	v_bfi_b32 v197, v247, v133, v155
	v_lshrrev_b64 v[132:133], v154, v[190:191]
	v_add_f32_e32 v133, v113, v160
	v_bfe_i32 v244, v132, 1, 1
	v_bfi_b32 v135, v243, v133, v155
	v_add_f32_e32 v133, v113, v161
	v_bfe_i32 v245, v132, 2, 1
	v_bfe_i32 v246, v132, 3, 1
	v_bfi_b32 v140, v244, v133, v155
	v_add_f32_e32 v133, v113, v162
	v_bfi_b32 v142, v245, v133, v155
	v_add_f32_e32 v133, v113, v163
	v_bfi_b32 v160, v246, v133, v155
	v_lshrrev_b64 v[132:133], v179, v[192:193]
	v_lshrrev_b32_e32 v133, v179, v192
	v_bfe_i32 v247, v133, 0, 1
	v_bfe_i32 v243, v132, 2, 1
	v_bfi_b32 v162, v247, v124, v155
	v_add_f32_e32 v124, v113, v125
	v_bfe_i32 v244, v132, 1, 1
	v_bfe_i32 v245, v132, 3, 1
	v_bfi_b32 v192, v244, v124, v155
	v_lshrrev_b64 v[124:125], v179, v[190:191]
	v_add_f32_e32 v125, v113, v128
	v_lshrrev_b32_e32 v128, v179, v190
	v_bfe_i32 v246, v128, 0, 1
	v_add_f32_e32 v128, v113, v129
	v_bfe_i32 v247, v124, 1, 1
	v_bfi_b32 v125, v246, v125, v155
	v_add_f32_e32 v129, v113, v130
	v_bfe_i32 v244, v124, 2, 1
	v_bfi_b32 v128, v247, v128, v155
	v_bfe_i32 v246, v124, 3, 1
	v_add_f32_e32 v130, v113, v131
	v_bfi_b32 v129, v244, v129, v155
	v_bfi_b32 v124, v246, v130, v155
	v_max3_f32 v130, v125, s79, v128
	v_max3_f32 v130, v130, v129, v124
	v_max3_f32 v130, v130, v135, v140
	v_max3_f32 v130, v130, v142, v160
	v_max3_f32 v130, v130, v134, v136
	v_max3_f32 v130, v130, v138, v156
	v_max3_f32 v130, v130, v158, v164
	v_max3_f32 v130, v130, v167, v183
	ds_bpermute_b32 v131, v159, v130
	s_waitcnt lgkmcnt(0)
	v_max_f32_e32 v131, v131, v131
	v_max_f32_e32 v130, v130, v131
	ds_bpermute_b32 v131, v184, v130
	v_bfi_b32 v126, v243, v126, v155
	s_waitcnt lgkmcnt(0)
	v_max3_f32 v182, v123, v130, v131
	v_sub_f32_e32 v241, v182, v123
	v_cmp_lt_f32_e64 s[98:99], 4.0, v241
	s_nop 1
	v_cndmask_b32_e64 v182, v123, v182, s[98:99]
	v_sub_f32_e32 v130, v123, v182
	v_sub_f32_e32 v123, v125, v182
	v_bfi_b32 v132, v245, v127, v155
	v_exp_f32_e32 v157, v123
	v_sub_f32_e32 v123, v128, v182
	v_max3_f32 v128, v162, s79, v192
	v_max3_f32 v128, v128, v126, v132
	v_exp_f32_e32 v143, v123
	v_sub_f32_e32 v123, v129, v182
	v_max3_f32 v128, v128, v194, v195
	v_exp_f32_e32 v141, v123
	v_sub_f32_e32 v123, v124, v182
	v_max3_f32 v128, v128, v196, v197
	v_exp_f32_e32 v139, v123
	v_sub_f32_e32 v123, v135, v182
	v_max3_f32 v128, v128, v186, v187
	v_exp_f32_e32 v137, v123
	v_sub_f32_e32 v123, v140, v182
	v_max3_f32 v128, v128, v188, v189
	v_exp_f32_e32 v135, v123
	v_sub_f32_e32 v123, v142, v182
	v_max3_f32 v128, v128, v168, v169
	v_exp_f32_e32 v133, v123
	v_sub_f32_e32 v123, v160, v182
	v_max3_f32 v128, v128, v166, v185
	v_exp_f32_e32 v131, v123
	v_sub_f32_e32 v123, v134, v182
	ds_bpermute_b32 v134, v159, v128
	v_sub_f32_e32 v124, v158, v182
	v_exp_f32_e32 v165, v124
	v_sub_f32_e32 v124, v164, v182
	v_exp_f32_e32 v161, v124
	s_waitcnt lgkmcnt(0)
	v_max_f32_e32 v134, v134, v134
	v_max_f32_e32 v128, v128, v134
	ds_bpermute_b32 v134, v184, v128
	v_sub_f32_e32 v124, v167, v182
	v_exp_f32_e32 v129, v123
	v_sub_f32_e32 v123, v136, v182
	v_exp_f32_e32 v167, v124
	v_sub_f32_e32 v124, v183, v182
	s_waitcnt lgkmcnt(0)
	v_max3_f32 v183, v122, v128, v134
	v_sub_f32_e32 v242, v183, v122
	v_cmp_lt_f32_e64 s[100:101], 4.0, v242
	s_nop 1
	v_cndmask_b32_e64 v183, v122, v183, s[100:101]
	v_exp_f32_e32 v127, v123
	v_sub_f32_e32 v123, v138, v182
	v_sub_f32_e32 v190, v122, v183
	v_sub_f32_e32 v122, v162, v183
	v_exp_f32_e32 v125, v123
	v_sub_f32_e32 v123, v156, v182
	v_exp_f32_e32 v156, v122
	v_sub_f32_e32 v122, v192, v183
	v_exp_f32_e32 v142, v122
	v_sub_f32_e32 v122, v126, v183
	v_exp_f32_e32 v140, v122
	v_sub_f32_e32 v122, v132, v183
	v_exp_f32_e32 v138, v122
	v_sub_f32_e32 v122, v194, v183
	v_exp_f32_e32 v136, v122
	v_sub_f32_e32 v122, v195, v183
	v_exp_f32_e32 v134, v122
	v_sub_f32_e32 v122, v196, v183
	v_sub_f32_e32 v160, v168, v183
	v_exp_f32_e32 v168, v190
	v_exp_f32_e32 v132, v122
	v_sub_f32_e32 v122, v197, v183
	v_exp_f32_e32 v158, v130
	v_exp_f32_e32 v130, v122
	v_sub_f32_e32 v122, v186, v183
	v_exp_f32_e32 v128, v122
	v_sub_f32_e32 v122, v187, v183
	v_exp_f32_e32 v126, v122
	v_sub_f32_e32 v122, v188, v183
	v_exp_f32_e32 v164, v160
	v_sub_f32_e32 v160, v169, v183
	v_sub_f32_e32 v162, v166, v183
	v_add_u32_e32 v169, s47, v180
	v_exp_f32_e32 v163, v124
	v_exp_f32_e32 v124, v122
	v_sub_f32_e32 v122, v189, v183
	v_exp_f32_e32 v166, v162
	v_sub_f32_e32 v162, v185, v183
	v_add_u32_e32 v185, 0x8000, v169
	v_add_u32_e32 v222, 0x8800, v169
	v_add_u32_e32 v223, 0x9000, v169
	v_add_u32_e32 v225, 0x9800, v169
	v_add_u32_e32 v230, 0xa000, v169
	v_add_u32_e32 v231, 0xa800, v169
	v_add_u32_e32 v232, 0xb000, v169
	v_add_u32_e32 v169, 0xb800, v169
	v_exp_f32_e32 v123, v123
	v_exp_f32_e32 v122, v122
	v_exp_f32_e32 v160, v160
	v_exp_f32_e32 v162, v162
	s_or_b64 s[98:99], s[98:99], s[100:101]
	s_cmp_eq_u64 s[98:99], 0
	s_cbranch_scc1 .Llazy_bf_skip
	v_pk_mul_f32 v[30:31], v[30:31], v[168:169] op_sel_hi:[1,0]
	v_pk_mul_f32 v[28:29], v[28:29], v[168:169] op_sel_hi:[1,0]
	v_pk_mul_f32 v[26:27], v[26:27], v[168:169] op_sel_hi:[1,0]
	v_pk_mul_f32 v[24:25], v[24:25], v[168:169] op_sel_hi:[1,0]
	v_pk_mul_f32 v[22:23], v[22:23], v[168:169] op_sel_hi:[1,0]
	v_pk_mul_f32 v[20:21], v[20:21], v[168:169] op_sel_hi:[1,0]
	v_pk_mul_f32 v[18:19], v[18:19], v[168:169] op_sel_hi:[1,0]
	v_pk_mul_f32 v[16:17], v[16:17], v[168:169] op_sel_hi:[1,0]
	v_pk_mul_f32 v[14:15], v[14:15], v[168:169] op_sel_hi:[1,0]
	v_pk_mul_f32 v[12:13], v[12:13], v[168:169] op_sel_hi:[1,0]
	v_pk_mul_f32 v[10:11], v[10:11], v[168:169] op_sel_hi:[1,0]
	v_pk_mul_f32 v[8:9], v[8:9], v[168:169] op_sel_hi:[1,0]
	v_pk_mul_f32 v[6:7], v[6:7], v[168:169] op_sel_hi:[1,0]
	v_pk_mul_f32 v[4:5], v[4:5], v[168:169] op_sel_hi:[1,0]
	v_pk_mul_f32 v[2:3], v[2:3], v[168:169] op_sel_hi:[1,0]
	v_pk_mul_f32 v[0:1], v[0:1], v[168:169] op_sel_hi:[1,0]
	v_pk_mul_f32 v[110:111], v[110:111], v[158:159] op_sel_hi:[1,0]
	v_pk_mul_f32 v[108:109], v[108:109], v[158:159] op_sel_hi:[1,0]
	v_pk_mul_f32 v[106:107], v[106:107], v[158:159] op_sel_hi:[1,0]
	v_pk_mul_f32 v[104:105], v[104:105], v[158:159] op_sel_hi:[1,0]
	v_pk_mul_f32 v[102:103], v[102:103], v[158:159] op_sel_hi:[1,0]
	v_pk_mul_f32 v[100:101], v[100:101], v[158:159] op_sel_hi:[1,0]
	v_pk_mul_f32 v[98:99], v[98:99], v[158:159] op_sel_hi:[1,0]
	v_pk_mul_f32 v[96:97], v[96:97], v[158:159] op_sel_hi:[1,0]
	v_pk_mul_f32 v[86:87], v[86:87], v[158:159] op_sel_hi:[1,0]
	v_pk_mul_f32 v[84:85], v[84:85], v[158:159] op_sel_hi:[1,0]
	v_pk_mul_f32 v[42:43], v[42:43], v[158:159] op_sel_hi:[1,0]
	v_pk_mul_f32 v[40:41], v[40:41], v[158:159] op_sel_hi:[1,0]
	v_pk_mul_f32 v[38:39], v[38:39], v[158:159] op_sel_hi:[1,0]
	v_pk_mul_f32 v[36:37], v[36:37], v[158:159] op_sel_hi:[1,0]
	v_pk_mul_f32 v[34:35], v[34:35], v[158:159] op_sel_hi:[1,0]
	v_pk_mul_f32 v[32:33], v[32:33], v[158:159] op_sel_hi:[1,0]
